# gated GEMM epilogues (P3/P4): 16-step load-wait-store ladders replaced by batched loads + one wait; on top of the spread-DMA attention
# baseline (speedup 1.0000x reference)
; __device__ __forceinline__ unsigned cvt_pk_bf16(float lo, float hi) { const f32x2_t v = {lo, hi}; const bf16x2_t r = __builtin_convertvector(v, bf16x2_t); return __builtin_bit_cast(unsigned, r); }
; __device__ __forceinline__ float bf_lo(unsigned w) { return __uint_as_float(w << 16); }
; __device__ __forceinline__ float bf_hi(unsigned w) { return __uint_as_float(w & 0xffff0000u); }
;     __device__ __forceinline__ void operator()(const f32x4 (&acc)[2][2][4][2], const Unit& u, int wr, int wc, int fr, int fq) const {
;         bf16_t* GA = (bf16_t*)(ws + WS_GA); const bf16_t* GB = (const bf16_t*)(ws + WS_GB); bf16_t* Y = (bf16_t*)(ws + WS_ZA);
;         const int row0 = u.pm * BM + wr * 64 + fr, col0 = u.pn * BM + wc * 32 + 8 * fq;
; #pragma unroll
;         for (int ai = 0; ai < 2; ++ai)
; #pragma unroll
;             for (int m = 0; m < 4; ++m) { const size_t off = (size_t)(row0 + ai * HALF + m * 16) * 1024 + col0;
; #pragma unroll
;                 for (int bj = 0; bj < 2; ++bj) { const f32x4 v0 = acc[ai][bj][m][0], v1 = acc[ai][bj][m][1];
;                     const u32x4 ga = *(const u32x4*)(GA + off + bj * HALF); u32x4 w;
;                     if (MODE == 0) {
;                         w.x = cvt_pk_bf16(v0[0] * bf_lo(ga.x), v0[1] * bf_hi(ga.x)); w.y = cvt_pk_bf16(v0[2] * bf_lo(ga.y), v0[3] * bf_hi(ga.y));
;                         w.z = cvt_pk_bf16(v1[0] * bf_lo(ga.z), v1[1] * bf_hi(ga.z)); w.w = cvt_pk_bf16(v1[2] * bf_lo(ga.w), v1[3] * bf_hi(ga.w));
;                         *(u32x4*)(GA + off + bj * HALF) = w;
.LBB0_88:
	v_mov_b32_e32 v138, v236
	s_lshl_b32 s14, s52, 8
	s_add_i32 s14, s14, s29
	v_and_or_b32 v140, v138, 15, s14
	s_lshl_b32 s14, s53, 8
	v_ashrrev_i32_e32 v138, 1, v138
	s_or_b32 s14, s14, s33
	v_and_b32_e32 v138, -8, v138
	v_add_u32_e32 v138, s14, v138
	v_ashrrev_i32_e32 v139, 31, v138
	v_ashrrev_i32_e32 v141, 31, v140
	v_lshl_add_u64 v[142:143], v[138:139], 1, s[38:39]
	v_lshlrev_b64 v[138:139], 11, v[140:141]
	v_lshl_add_u64 v[138:139], v[142:143], 0, v[138:139]
	s_mov_b64 s[52:53], -1
	s_mov_b64 s[14:15], 0
	v_lshl_add_u64 v[156:157], v[138:139], 0, s[14:15]
	global_load_dwordx4 v[162:165], v[156:157], off
	global_load_dwordx4 v[166:169], v[156:157], off offset:256
	s_mov_b64 s[14:15], 0x8000
	v_lshl_add_u64 v[156:157], v[138:139], 0, s[14:15]
	global_load_dwordx4 v[170:173], v[156:157], off
	global_load_dwordx4 v[174:177], v[156:157], off offset:256
	s_mov_b64 s[14:15], 0x10000
	v_lshl_add_u64 v[156:157], v[138:139], 0, s[14:15]
	global_load_dwordx4 v[178:181], v[156:157], off
	global_load_dwordx4 v[182:185], v[156:157], off offset:256
	s_mov_b64 s[14:15], 0x18000
	v_lshl_add_u64 v[156:157], v[138:139], 0, s[14:15]
	global_load_dwordx4 v[186:189], v[156:157], off
	global_load_dwordx4 v[190:193], v[156:157], off offset:256
	s_mov_b64 s[14:15], 0x40000
	v_lshl_add_u64 v[156:157], v[138:139], 0, s[14:15]
	global_load_dwordx4 v[194:197], v[156:157], off
	global_load_dwordx4 v[198:201], v[156:157], off offset:256
	s_mov_b64 s[14:15], 0x48000
	v_lshl_add_u64 v[156:157], v[138:139], 0, s[14:15]
	global_load_dwordx4 v[202:205], v[156:157], off
	global_load_dwordx4 v[206:209], v[156:157], off offset:256
	s_mov_b64 s[14:15], 0x50000
	v_lshl_add_u64 v[156:157], v[138:139], 0, s[14:15]
	global_load_dwordx4 v[210:213], v[156:157], off
	global_load_dwordx4 v[146:149], v[156:157], off offset:256
	s_mov_b64 s[14:15], 0x58000
	v_lshl_add_u64 v[156:157], v[138:139], 0, s[14:15]
	global_load_dwordx4 v[150:153], v[156:157], off
	global_load_dwordx4 v[140:143], v[156:157], off offset:256
	s_waitcnt vmcnt(0) lgkmcnt(0)
	s_mov_b64 s[14:15], 0
	v_lshl_add_u64 v[156:157], v[138:139], 0, s[14:15]
	v_lshlrev_b32_e32 v158, 16, v162
	v_and_b32_e32 v159, 0xffff0000, v162
	v_pk_mul_f32 v[124:125], v[124:125], v[158:159]
	v_lshlrev_b32_e32 v158, 16, v163
	v_and_b32_e32 v159, 0xffff0000, v163
	v_pk_mul_f32 v[126:127], v[126:127], v[158:159]
	v_lshlrev_b32_e32 v158, 16, v164
	v_and_b32_e32 v159, 0xffff0000, v164
	v_pk_mul_f32 v[120:121], v[120:121], v[158:159]
	v_lshlrev_b32_e32 v158, 16, v165
	v_and_b32_e32 v159, 0xffff0000, v165
	v_pk_mul_f32 v[122:123], v[122:123], v[158:159]
	v_cvt_pk_bf16_f32 v124, v124, v125
	v_cvt_pk_bf16_f32 v125, v126, v127
	v_cvt_pk_bf16_f32 v126, v120, v121
	v_cvt_pk_bf16_f32 v127, v122, v123
	global_store_dwordx4 v[156:157], v[124:127], off
	v_lshlrev_b32_e32 v158, 16, v166
	v_and_b32_e32 v159, 0xffff0000, v166
	v_pk_mul_f32 v[116:117], v[116:117], v[158:159]
	v_lshlrev_b32_e32 v158, 16, v167
	v_and_b32_e32 v159, 0xffff0000, v167
	v_pk_mul_f32 v[118:119], v[118:119], v[158:159]
	v_lshlrev_b32_e32 v158, 16, v168
	v_and_b32_e32 v159, 0xffff0000, v168
	v_pk_mul_f32 v[112:113], v[112:113], v[158:159]
	v_lshlrev_b32_e32 v158, 16, v169
	v_and_b32_e32 v159, 0xffff0000, v169
	v_pk_mul_f32 v[114:115], v[114:115], v[158:159]
	v_cvt_pk_bf16_f32 v116, v116, v117
	v_cvt_pk_bf16_f32 v117, v118, v119
	v_cvt_pk_bf16_f32 v118, v112, v113
	v_cvt_pk_bf16_f32 v119, v114, v115
	global_store_dwordx4 v[156:157], v[116:119], off offset:256
	s_mov_b64 s[14:15], 0x8000
	v_lshl_add_u64 v[156:157], v[138:139], 0, s[14:15]
	v_lshlrev_b32_e32 v158, 16, v170
	v_and_b32_e32 v159, 0xffff0000, v170
	v_pk_mul_f32 v[108:109], v[108:109], v[158:159]
	v_lshlrev_b32_e32 v158, 16, v171
	v_and_b32_e32 v159, 0xffff0000, v171
	v_pk_mul_f32 v[110:111], v[110:111], v[158:159]
	v_lshlrev_b32_e32 v158, 16, v172
	v_and_b32_e32 v159, 0xffff0000, v172
	v_pk_mul_f32 v[104:105], v[104:105], v[158:159]
	v_lshlrev_b32_e32 v158, 16, v173
	v_and_b32_e32 v159, 0xffff0000, v173
	v_pk_mul_f32 v[106:107], v[106:107], v[158:159]
	v_cvt_pk_bf16_f32 v108, v108, v109
	v_cvt_pk_bf16_f32 v109, v110, v111
	v_cvt_pk_bf16_f32 v110, v104, v105
	v_cvt_pk_bf16_f32 v111, v106, v107
	global_store_dwordx4 v[156:157], v[108:111], off
	v_lshlrev_b32_e32 v158, 16, v174
	v_and_b32_e32 v159, 0xffff0000, v174
	v_pk_mul_f32 v[100:101], v[100:101], v[158:159]
	v_lshlrev_b32_e32 v158, 16, v175
	v_and_b32_e32 v159, 0xffff0000, v175
	v_pk_mul_f32 v[102:103], v[102:103], v[158:159]
	v_lshlrev_b32_e32 v158, 16, v176
	v_and_b32_e32 v159, 0xffff0000, v176
	v_pk_mul_f32 v[96:97], v[96:97], v[158:159]
	v_lshlrev_b32_e32 v158, 16, v177
	v_and_b32_e32 v159, 0xffff0000, v177
	v_pk_mul_f32 v[98:99], v[98:99], v[158:159]
	v_cvt_pk_bf16_f32 v100, v100, v101
	v_cvt_pk_bf16_f32 v101, v102, v103
	v_cvt_pk_bf16_f32 v102, v96, v97
	v_cvt_pk_bf16_f32 v103, v98, v99
	global_store_dwordx4 v[156:157], v[100:103], off offset:256
	s_mov_b64 s[14:15], 0x10000
	v_lshl_add_u64 v[156:157], v[138:139], 0, s[14:15]
	v_lshlrev_b32_e32 v158, 16, v178
	v_and_b32_e32 v159, 0xffff0000, v178
	v_pk_mul_f32 v[92:93], v[92:93], v[158:159]
	v_lshlrev_b32_e32 v158, 16, v179
	v_and_b32_e32 v159, 0xffff0000, v179
	v_pk_mul_f32 v[94:95], v[94:95], v[158:159]
	v_lshlrev_b32_e32 v158, 16, v180
	v_and_b32_e32 v159, 0xffff0000, v180
	v_pk_mul_f32 v[88:89], v[88:89], v[158:159]
	v_lshlrev_b32_e32 v158, 16, v181
	v_and_b32_e32 v159, 0xffff0000, v181
	v_pk_mul_f32 v[90:91], v[90:91], v[158:159]
	v_cvt_pk_bf16_f32 v92, v92, v93
	v_cvt_pk_bf16_f32 v93, v94, v95
	v_cvt_pk_bf16_f32 v94, v88, v89
	v_cvt_pk_bf16_f32 v95, v90, v91
	global_store_dwordx4 v[156:157], v[92:95], off
; __device__ __forceinline__ unsigned cvt_pk_bf16(float lo, float hi) { const f32x2_t v = {lo, hi}; const bf16x2_t r = __builtin_convertvector(v, bf16x2_t); return __builtin_bit_cast(unsigned, r); }
; __device__ __forceinline__ float bf_lo(unsigned w) { return __uint_as_float(w << 16); }
; __device__ __forceinline__ float bf_hi(unsigned w) { return __uint_as_float(w & 0xffff0000u); }
;     __device__ __forceinline__ void operator()(const f32x4 (&acc)[2][2][4][2], const Unit& u, int wr, int wc, int fr, int fq) const {
;     ...
;             for (int m = 0; m < 4; ++m) { const size_t off = (size_t)(row0 + ai * HALF + m * 16) * 1024 + col0;
; #pragma unroll
;                 for (int bj = 0; bj < 2; ++bj) { const f32x4 v0 = acc[ai][bj][m][0], v1 = acc[ai][bj][m][1];
;                     const u32x4 ga = *(const u32x4*)(GA + off + bj * HALF); u32x4 w;
;                     if (MODE == 0) {
;                         w.x = cvt_pk_bf16(v0[0] * bf_lo(ga.x), v0[1] * bf_hi(ga.x)); w.y = cvt_pk_bf16(v0[2] * bf_lo(ga.y), v0[3] * bf_hi(ga.y));
;                         w.z = cvt_pk_bf16(v1[0] * bf_lo(ga.z), v1[1] * bf_hi(ga.z)); w.w = cvt_pk_bf16(v1[2] * bf_lo(ga.w), v1[3] * bf_hi(ga.w));
;                         *(u32x4*)(GA + off + bj * HALF) = w;
	v_lshlrev_b32_e32 v158, 16, v182
	v_and_b32_e32 v159, 0xffff0000, v182
	v_pk_mul_f32 v[84:85], v[84:85], v[158:159]
	v_lshlrev_b32_e32 v158, 16, v183
	v_and_b32_e32 v159, 0xffff0000, v183
	v_pk_mul_f32 v[86:87], v[86:87], v[158:159]
	v_lshlrev_b32_e32 v158, 16, v184
	v_and_b32_e32 v159, 0xffff0000, v184
	v_pk_mul_f32 v[80:81], v[80:81], v[158:159]
	v_lshlrev_b32_e32 v158, 16, v185
	v_and_b32_e32 v159, 0xffff0000, v185
	v_pk_mul_f32 v[82:83], v[82:83], v[158:159]
	v_cvt_pk_bf16_f32 v84, v84, v85
	v_cvt_pk_bf16_f32 v85, v86, v87
	v_cvt_pk_bf16_f32 v86, v80, v81
	v_cvt_pk_bf16_f32 v87, v82, v83
	global_store_dwordx4 v[156:157], v[84:87], off offset:256
	s_mov_b64 s[14:15], 0x18000
	v_lshl_add_u64 v[156:157], v[138:139], 0, s[14:15]
	v_lshlrev_b32_e32 v158, 16, v186
	v_and_b32_e32 v159, 0xffff0000, v186
	v_pk_mul_f32 v[76:77], v[76:77], v[158:159]
	v_lshlrev_b32_e32 v158, 16, v187
	v_and_b32_e32 v159, 0xffff0000, v187
	v_pk_mul_f32 v[78:79], v[78:79], v[158:159]
	v_lshlrev_b32_e32 v158, 16, v188
	v_and_b32_e32 v159, 0xffff0000, v188
	v_pk_mul_f32 v[72:73], v[72:73], v[158:159]
	v_lshlrev_b32_e32 v158, 16, v189
	v_and_b32_e32 v159, 0xffff0000, v189
	v_pk_mul_f32 v[74:75], v[74:75], v[158:159]
	v_cvt_pk_bf16_f32 v76, v76, v77
	v_cvt_pk_bf16_f32 v77, v78, v79
	v_cvt_pk_bf16_f32 v78, v72, v73
	v_cvt_pk_bf16_f32 v79, v74, v75
	global_store_dwordx4 v[156:157], v[76:79], off
	v_lshlrev_b32_e32 v158, 16, v190
	v_and_b32_e32 v159, 0xffff0000, v190
	v_pk_mul_f32 v[68:69], v[68:69], v[158:159]
	v_lshlrev_b32_e32 v158, 16, v191
	v_and_b32_e32 v159, 0xffff0000, v191
	v_pk_mul_f32 v[70:71], v[70:71], v[158:159]
	v_lshlrev_b32_e32 v158, 16, v192
	v_and_b32_e32 v159, 0xffff0000, v192
	v_pk_mul_f32 v[64:65], v[64:65], v[158:159]
	v_lshlrev_b32_e32 v158, 16, v193
	v_and_b32_e32 v159, 0xffff0000, v193
	v_pk_mul_f32 v[66:67], v[66:67], v[158:159]
	v_cvt_pk_bf16_f32 v68, v68, v69
	v_cvt_pk_bf16_f32 v69, v70, v71
	v_cvt_pk_bf16_f32 v70, v64, v65
	v_cvt_pk_bf16_f32 v71, v66, v67
	global_store_dwordx4 v[156:157], v[68:71], off offset:256
	s_mov_b64 s[14:15], 0x40000
	v_lshl_add_u64 v[156:157], v[138:139], 0, s[14:15]
	v_lshlrev_b32_e32 v158, 16, v194
	v_and_b32_e32 v159, 0xffff0000, v194
	v_pk_mul_f32 v[60:61], v[60:61], v[158:159]
	v_lshlrev_b32_e32 v158, 16, v195
	v_and_b32_e32 v159, 0xffff0000, v195
	v_pk_mul_f32 v[62:63], v[62:63], v[158:159]
	v_lshlrev_b32_e32 v158, 16, v196
	v_and_b32_e32 v159, 0xffff0000, v196
	v_pk_mul_f32 v[56:57], v[56:57], v[158:159]
	v_lshlrev_b32_e32 v158, 16, v197
	v_and_b32_e32 v159, 0xffff0000, v197
	v_pk_mul_f32 v[58:59], v[58:59], v[158:159]
	v_cvt_pk_bf16_f32 v60, v60, v61
	v_cvt_pk_bf16_f32 v61, v62, v63
	v_cvt_pk_bf16_f32 v62, v56, v57
	v_cvt_pk_bf16_f32 v63, v58, v59
	global_store_dwordx4 v[156:157], v[60:63], off
	v_lshlrev_b32_e32 v158, 16, v198
	v_and_b32_e32 v159, 0xffff0000, v198
	v_pk_mul_f32 v[52:53], v[52:53], v[158:159]
	v_lshlrev_b32_e32 v158, 16, v199
	v_and_b32_e32 v159, 0xffff0000, v199
	v_pk_mul_f32 v[54:55], v[54:55], v[158:159]
	v_lshlrev_b32_e32 v158, 16, v200
	v_and_b32_e32 v159, 0xffff0000, v200
	v_pk_mul_f32 v[48:49], v[48:49], v[158:159]
	v_lshlrev_b32_e32 v158, 16, v201
	v_and_b32_e32 v159, 0xffff0000, v201
	v_pk_mul_f32 v[50:51], v[50:51], v[158:159]
	v_cvt_pk_bf16_f32 v52, v52, v53
	v_cvt_pk_bf16_f32 v53, v54, v55
	v_cvt_pk_bf16_f32 v54, v48, v49
	v_cvt_pk_bf16_f32 v55, v50, v51
	global_store_dwordx4 v[156:157], v[52:55], off offset:256
	s_mov_b64 s[14:15], 0x48000
	v_lshl_add_u64 v[156:157], v[138:139], 0, s[14:15]
	v_lshlrev_b32_e32 v158, 16, v202
	v_and_b32_e32 v159, 0xffff0000, v202
	v_pk_mul_f32 v[44:45], v[44:45], v[158:159]
	v_lshlrev_b32_e32 v158, 16, v203
	v_and_b32_e32 v159, 0xffff0000, v203
	v_pk_mul_f32 v[46:47], v[46:47], v[158:159]
	v_lshlrev_b32_e32 v158, 16, v204
	v_and_b32_e32 v159, 0xffff0000, v204
	v_pk_mul_f32 v[40:41], v[40:41], v[158:159]
; __device__ __forceinline__ unsigned cvt_pk_bf16(float lo, float hi) { const f32x2_t v = {lo, hi}; const bf16x2_t r = __builtin_convertvector(v, bf16x2_t); return __builtin_bit_cast(unsigned, r); }
; __device__ __forceinline__ float bf_lo(unsigned w) { return __uint_as_float(w << 16); }
; __device__ __forceinline__ float bf_hi(unsigned w) { return __uint_as_float(w & 0xffff0000u); }
;     __device__ __forceinline__ void operator()(const f32x4 (&acc)[2][2][4][2], const Unit& u, int wr, int wc, int fr, int fq) const {
;     ...
;             for (int m = 0; m < 4; ++m) { const size_t off = (size_t)(row0 + ai * HALF + m * 16) * 1024 + col0;
; #pragma unroll
;                 for (int bj = 0; bj < 2; ++bj) { const f32x4 v0 = acc[ai][bj][m][0], v1 = acc[ai][bj][m][1];
;                     const u32x4 ga = *(const u32x4*)(GA + off + bj * HALF); u32x4 w;
;                     if (MODE == 0) {
;                         w.x = cvt_pk_bf16(v0[0] * bf_lo(ga.x), v0[1] * bf_hi(ga.x)); w.y = cvt_pk_bf16(v0[2] * bf_lo(ga.y), v0[3] * bf_hi(ga.y));
;                         w.z = cvt_pk_bf16(v1[0] * bf_lo(ga.z), v1[1] * bf_hi(ga.z)); w.w = cvt_pk_bf16(v1[2] * bf_lo(ga.w), v1[3] * bf_hi(ga.w));
;                         *(u32x4*)(GA + off + bj * HALF) = w;
	v_lshlrev_b32_e32 v158, 16, v205
	v_and_b32_e32 v159, 0xffff0000, v205
	v_pk_mul_f32 v[42:43], v[42:43], v[158:159]
	v_cvt_pk_bf16_f32 v44, v44, v45
	v_cvt_pk_bf16_f32 v45, v46, v47
	v_cvt_pk_bf16_f32 v46, v40, v41
	v_cvt_pk_bf16_f32 v47, v42, v43
	global_store_dwordx4 v[156:157], v[44:47], off
	v_lshlrev_b32_e32 v158, 16, v206
	v_and_b32_e32 v159, 0xffff0000, v206
	v_pk_mul_f32 v[36:37], v[36:37], v[158:159]
	v_lshlrev_b32_e32 v158, 16, v207
	v_and_b32_e32 v159, 0xffff0000, v207
	v_pk_mul_f32 v[38:39], v[38:39], v[158:159]
	v_lshlrev_b32_e32 v158, 16, v208
	v_and_b32_e32 v159, 0xffff0000, v208
	v_pk_mul_f32 v[32:33], v[32:33], v[158:159]
	v_lshlrev_b32_e32 v158, 16, v209
	v_and_b32_e32 v159, 0xffff0000, v209
	v_pk_mul_f32 v[34:35], v[34:35], v[158:159]
	v_cvt_pk_bf16_f32 v36, v36, v37
	v_cvt_pk_bf16_f32 v37, v38, v39
	v_cvt_pk_bf16_f32 v38, v32, v33
	v_cvt_pk_bf16_f32 v39, v34, v35
	global_store_dwordx4 v[156:157], v[36:39], off offset:256
	s_mov_b64 s[14:15], 0x50000
	v_lshl_add_u64 v[156:157], v[138:139], 0, s[14:15]
	v_lshlrev_b32_e32 v158, 16, v210
	v_and_b32_e32 v159, 0xffff0000, v210
	v_pk_mul_f32 v[28:29], v[28:29], v[158:159]
	v_lshlrev_b32_e32 v158, 16, v211
	v_and_b32_e32 v159, 0xffff0000, v211
	v_pk_mul_f32 v[30:31], v[30:31], v[158:159]
	v_lshlrev_b32_e32 v158, 16, v212
	v_and_b32_e32 v159, 0xffff0000, v212
	v_pk_mul_f32 v[24:25], v[24:25], v[158:159]
	v_lshlrev_b32_e32 v158, 16, v213
	v_and_b32_e32 v159, 0xffff0000, v213
	v_pk_mul_f32 v[26:27], v[26:27], v[158:159]
	v_cvt_pk_bf16_f32 v28, v28, v29
	v_cvt_pk_bf16_f32 v29, v30, v31
	v_cvt_pk_bf16_f32 v30, v24, v25
	v_cvt_pk_bf16_f32 v31, v26, v27
	global_store_dwordx4 v[156:157], v[28:31], off
	v_lshlrev_b32_e32 v158, 16, v146
	v_and_b32_e32 v159, 0xffff0000, v146
	v_pk_mul_f32 v[20:21], v[20:21], v[158:159]
	v_lshlrev_b32_e32 v158, 16, v147
	v_and_b32_e32 v159, 0xffff0000, v147
	v_pk_mul_f32 v[22:23], v[22:23], v[158:159]
	v_lshlrev_b32_e32 v158, 16, v148
	v_and_b32_e32 v159, 0xffff0000, v148
	v_pk_mul_f32 v[16:17], v[16:17], v[158:159]
	v_lshlrev_b32_e32 v158, 16, v149
	v_and_b32_e32 v159, 0xffff0000, v149
	v_pk_mul_f32 v[18:19], v[18:19], v[158:159]
	v_cvt_pk_bf16_f32 v20, v20, v21
	v_cvt_pk_bf16_f32 v21, v22, v23
	v_cvt_pk_bf16_f32 v22, v16, v17
	v_cvt_pk_bf16_f32 v23, v18, v19
	global_store_dwordx4 v[156:157], v[20:23], off offset:256
	s_mov_b64 s[14:15], 0x58000
	v_lshl_add_u64 v[156:157], v[138:139], 0, s[14:15]
	v_lshlrev_b32_e32 v158, 16, v150
	v_and_b32_e32 v159, 0xffff0000, v150
	v_pk_mul_f32 v[12:13], v[12:13], v[158:159]
	v_lshlrev_b32_e32 v158, 16, v151
	v_and_b32_e32 v159, 0xffff0000, v151
	v_pk_mul_f32 v[14:15], v[14:15], v[158:159]
	v_lshlrev_b32_e32 v158, 16, v152
	v_and_b32_e32 v159, 0xffff0000, v152
	v_pk_mul_f32 v[8:9], v[8:9], v[158:159]
	v_lshlrev_b32_e32 v158, 16, v153
	v_and_b32_e32 v159, 0xffff0000, v153
	v_pk_mul_f32 v[10:11], v[10:11], v[158:159]
	v_cvt_pk_bf16_f32 v12, v12, v13
	v_cvt_pk_bf16_f32 v13, v14, v15
	v_cvt_pk_bf16_f32 v14, v8, v9
	v_cvt_pk_bf16_f32 v15, v10, v11
	global_store_dwordx4 v[156:157], v[12:15], off
	v_lshlrev_b32_e32 v158, 16, v140
	v_and_b32_e32 v159, 0xffff0000, v140
	v_pk_mul_f32 v[4:5], v[4:5], v[158:159]
	v_lshlrev_b32_e32 v158, 16, v141
	v_and_b32_e32 v159, 0xffff0000, v141
	v_pk_mul_f32 v[6:7], v[6:7], v[158:159]
	v_lshlrev_b32_e32 v158, 16, v142
	v_and_b32_e32 v159, 0xffff0000, v142
	v_pk_mul_f32 v[0:1], v[0:1], v[158:159]
	v_lshlrev_b32_e32 v158, 16, v143
	v_and_b32_e32 v159, 0xffff0000, v143
	v_pk_mul_f32 v[2:3], v[2:3], v[158:159]
	v_cvt_pk_bf16_f32 v4, v4, v5
	v_cvt_pk_bf16_f32 v5, v6, v7
	v_cvt_pk_bf16_f32 v6, v0, v1
	v_cvt_pk_bf16_f32 v7, v2, v3
	global_store_dwordx4 v[156:157], v[4:7], off offset:256
	s_andn2_b64 vcc, exec, s[42:43]
	s_cbranch_vccnz .LBB0_81
	s_and_b64 vcc, exec, s[40:41]
	s_cbranch_vccnz .LBB0_80
	s_barrier
	s_branch .LBB0_80

; __device__ __forceinline__ unsigned cvt_pk_bf16(float lo, float hi) { const f32x2_t v = {lo, hi}; const bf16x2_t r = __builtin_convertvector(v, bf16x2_t); return __builtin_bit_cast(unsigned, r); }
; __device__ __forceinline__ float bf_lo(unsigned w) { return __uint_as_float(w << 16); }
; __device__ __forceinline__ float bf_hi(unsigned w) { return __uint_as_float(w & 0xffff0000u); }
;     __device__ __forceinline__ void operator()(const f32x4 (&acc)[2][2][4][2], const Unit& u, int wr, int wc, int fr, int fq) const {
;         bf16_t* GA = (bf16_t*)(ws + WS_GA); const bf16_t* GB = (const bf16_t*)(ws + WS_GB); bf16_t* Y = (bf16_t*)(ws + WS_ZA);
;         const int row0 = u.pm * BM + wr * 64 + fr, col0 = u.pn * BM + wc * 32 + 8 * fq;
; #pragma unroll
;         for (int ai = 0; ai < 2; ++ai)
; #pragma unroll
;             for (int m = 0; m < 4; ++m) { const size_t off = (size_t)(row0 + ai * HALF + m * 16) * 1024 + col0;
; #pragma unroll
;                 for (int bj = 0; bj < 2; ++bj) { const f32x4 v0 = acc[ai][bj][m][0], v1 = acc[ai][bj][m][1];
;                     const u32x4 ga = *(const u32x4*)(GA + off + bj * HALF); u32x4 w;
;                     if (MODE == 0) {
;                         w.x = cvt_pk_bf16(v0[0] * bf_lo(ga.x), v0[1] * bf_hi(ga.x)); w.y = cvt_pk_bf16(v0[2] * bf_lo(ga.y), v0[3] * bf_hi(ga.y));
;                         w.z = cvt_pk_bf16(v1[0] * bf_lo(ga.z), v1[1] * bf_hi(ga.z)); w.w = cvt_pk_bf16(v1[2] * bf_lo(ga.w), v1[3] * bf_hi(ga.w));
;                         *(u32x4*)(GA + off + bj * HALF) = w;
;                     } else {
;                         const u32x4 gb = *(const u32x4*)(GB + off + bj * HALF);
;                         w.x = cvt_pk_bf16(bf_lo(ga.x) + v0[0] * bf_lo(gb.x), bf_hi(ga.x) + v0[1] * bf_hi(gb.x)); w.y = cvt_pk_bf16(bf_lo(ga.y) + v0[2] * bf_lo(gb.y), bf_hi(ga.y) + v0[3] * bf_hi(gb.y));
;                         w.z = cvt_pk_bf16(bf_lo(ga.z) + v1[0] * bf_lo(gb.z), bf_hi(ga.z) + v1[1] * bf_hi(gb.z)); w.w = cvt_pk_bf16(bf_lo(ga.w) + v1[2] * bf_lo(gb.w), bf_hi(ga.w) + v1[3] * bf_hi(gb.w));
;                         *(u32x4*)(Y + off + bj * HALF) = w;
.LBB0_104:
	v_mov_b32_e32 v138, v236
	s_lshl_b32 s14, s56, 8
	s_add_i32 s14, s14, s29
	v_and_or_b32 v142, v138, 15, s14
	s_lshl_b32 s14, s54, 8
	v_ashrrev_i32_e32 v138, 1, v138
	s_or_b32 s14, s14, s33
	v_and_b32_e32 v138, -8, v138
	v_add_u32_e32 v140, s14, v138
	v_ashrrev_i32_e32 v143, 31, v142
	v_ashrrev_i32_e32 v141, 31, v140
	v_lshlrev_b64 v[138:139], 10, v[142:143]
	v_lshl_add_u64 v[138:139], v[138:139], 0, v[140:141]
	v_lshlrev_b64 v[138:139], 1, v[138:139]
	s_mov_b64 s[54:55], -1
	s_mov_b64 s[14:15], 0
	v_lshl_add_u64 v[158:159], v[138:139], 0, s[14:15]
	v_lshl_add_u64 v[154:155], v[158:159], 0, s[24:25]
	v_lshl_add_u64 v[156:157], v[158:159], 0, s[38:39]
	global_load_dwordx4 v[162:165], v[154:155], off
	global_load_dwordx4 v[166:169], v[156:157], off
	global_load_dwordx4 v[170:173], v[154:155], off offset:256
	global_load_dwordx4 v[174:177], v[156:157], off offset:256
	s_mov_b64 s[14:15], 0x8000
	v_lshl_add_u64 v[158:159], v[138:139], 0, s[14:15]
	v_lshl_add_u64 v[154:155], v[158:159], 0, s[24:25]
	v_lshl_add_u64 v[156:157], v[158:159], 0, s[38:39]
	global_load_dwordx4 v[178:181], v[154:155], off
	global_load_dwordx4 v[182:185], v[156:157], off
	global_load_dwordx4 v[186:189], v[154:155], off offset:256
	global_load_dwordx4 v[190:193], v[156:157], off offset:256
	s_mov_b64 s[14:15], 0x10000
	v_lshl_add_u64 v[158:159], v[138:139], 0, s[14:15]
	v_lshl_add_u64 v[154:155], v[158:159], 0, s[24:25]
	v_lshl_add_u64 v[156:157], v[158:159], 0, s[38:39]
	global_load_dwordx4 v[194:197], v[154:155], off
	global_load_dwordx4 v[198:201], v[156:157], off
	global_load_dwordx4 v[202:205], v[154:155], off offset:256
	global_load_dwordx4 v[206:209], v[156:157], off offset:256
	s_mov_b64 s[14:15], 0x18000
	v_lshl_add_u64 v[158:159], v[138:139], 0, s[14:15]
	v_lshl_add_u64 v[154:155], v[158:159], 0, s[24:25]
	v_lshl_add_u64 v[156:157], v[158:159], 0, s[38:39]
	global_load_dwordx4 v[210:213], v[154:155], off
	global_load_dwordx4 v[146:149], v[156:157], off
	global_load_dwordx4 v[150:153], v[154:155], off offset:256
	global_load_dwordx4 v[140:143], v[156:157], off offset:256
	s_waitcnt vmcnt(0) lgkmcnt(0)
	s_mov_b64 s[14:15], 0
	v_lshl_add_u64 v[158:159], v[138:139], 0, s[14:15]
	v_lshl_add_u64 v[158:159], v[158:159], 0, s[44:45]
	v_lshlrev_b32_e32 v154, 16, v162
	v_and_b32_e32 v155, 0xffff0000, v162
	v_lshlrev_b32_e32 v156, 16, v166
	v_and_b32_e32 v157, 0xffff0000, v166
	v_pk_fma_f32 v[124:125], v[124:125], v[156:157], v[154:155]
	v_lshlrev_b32_e32 v154, 16, v163
	v_and_b32_e32 v155, 0xffff0000, v163
	v_lshlrev_b32_e32 v156, 16, v167
	v_and_b32_e32 v157, 0xffff0000, v167
	v_pk_fma_f32 v[126:127], v[126:127], v[156:157], v[154:155]
	v_lshlrev_b32_e32 v154, 16, v164
	v_and_b32_e32 v155, 0xffff0000, v164
	v_lshlrev_b32_e32 v156, 16, v168
	v_and_b32_e32 v157, 0xffff0000, v168
	v_pk_fma_f32 v[120:121], v[120:121], v[156:157], v[154:155]
	v_lshlrev_b32_e32 v154, 16, v165
	v_and_b32_e32 v155, 0xffff0000, v165
	v_lshlrev_b32_e32 v156, 16, v169
	v_and_b32_e32 v157, 0xffff0000, v169
	v_pk_fma_f32 v[122:123], v[122:123], v[156:157], v[154:155]
	v_cvt_pk_bf16_f32 v124, v124, v125
	v_cvt_pk_bf16_f32 v125, v126, v127
	v_cvt_pk_bf16_f32 v126, v120, v121
	v_cvt_pk_bf16_f32 v127, v122, v123
	global_store_dwordx4 v[158:159], v[124:127], off
	v_lshlrev_b32_e32 v154, 16, v170
	v_and_b32_e32 v155, 0xffff0000, v170
	v_lshlrev_b32_e32 v156, 16, v174
	v_and_b32_e32 v157, 0xffff0000, v174
	v_pk_fma_f32 v[116:117], v[116:117], v[156:157], v[154:155]
	v_lshlrev_b32_e32 v154, 16, v171
	v_and_b32_e32 v155, 0xffff0000, v171
	v_lshlrev_b32_e32 v156, 16, v175
	v_and_b32_e32 v157, 0xffff0000, v175
	v_pk_fma_f32 v[118:119], v[118:119], v[156:157], v[154:155]
	v_lshlrev_b32_e32 v154, 16, v172
	v_and_b32_e32 v155, 0xffff0000, v172
	v_lshlrev_b32_e32 v156, 16, v176
	v_and_b32_e32 v157, 0xffff0000, v176
	v_pk_fma_f32 v[112:113], v[112:113], v[156:157], v[154:155]
	v_lshlrev_b32_e32 v154, 16, v173
	v_and_b32_e32 v155, 0xffff0000, v173
	v_lshlrev_b32_e32 v156, 16, v177
	v_and_b32_e32 v157, 0xffff0000, v177
	v_pk_fma_f32 v[114:115], v[114:115], v[156:157], v[154:155]
	v_cvt_pk_bf16_f32 v116, v116, v117
	v_cvt_pk_bf16_f32 v117, v118, v119
	v_cvt_pk_bf16_f32 v118, v112, v113
	v_cvt_pk_bf16_f32 v119, v114, v115
	global_store_dwordx4 v[158:159], v[116:119], off offset:256
	s_mov_b64 s[14:15], 0x8000
	v_lshl_add_u64 v[158:159], v[138:139], 0, s[14:15]
	v_lshl_add_u64 v[158:159], v[158:159], 0, s[44:45]
	v_lshlrev_b32_e32 v154, 16, v178
	v_and_b32_e32 v155, 0xffff0000, v178
	v_lshlrev_b32_e32 v156, 16, v182
	v_and_b32_e32 v157, 0xffff0000, v182
	v_pk_fma_f32 v[108:109], v[108:109], v[156:157], v[154:155]
	v_lshlrev_b32_e32 v154, 16, v179
	v_and_b32_e32 v155, 0xffff0000, v179
	v_lshlrev_b32_e32 v156, 16, v183
	v_and_b32_e32 v157, 0xffff0000, v183
	v_pk_fma_f32 v[110:111], v[110:111], v[156:157], v[154:155]
	v_lshlrev_b32_e32 v154, 16, v180
	v_and_b32_e32 v155, 0xffff0000, v180
	v_lshlrev_b32_e32 v156, 16, v184
	v_and_b32_e32 v157, 0xffff0000, v184
	v_pk_fma_f32 v[104:105], v[104:105], v[156:157], v[154:155]
	v_lshlrev_b32_e32 v154, 16, v181
	v_and_b32_e32 v155, 0xffff0000, v181
	v_lshlrev_b32_e32 v156, 16, v185
	v_and_b32_e32 v157, 0xffff0000, v185
	v_pk_fma_f32 v[106:107], v[106:107], v[156:157], v[154:155]
	v_cvt_pk_bf16_f32 v108, v108, v109
	v_cvt_pk_bf16_f32 v109, v110, v111
	v_cvt_pk_bf16_f32 v110, v104, v105
	v_cvt_pk_bf16_f32 v111, v106, v107
	global_store_dwordx4 v[158:159], v[108:111], off
	v_lshlrev_b32_e32 v154, 16, v186
	v_and_b32_e32 v155, 0xffff0000, v186
	v_lshlrev_b32_e32 v156, 16, v190
	v_and_b32_e32 v157, 0xffff0000, v190
	v_pk_fma_f32 v[100:101], v[100:101], v[156:157], v[154:155]
; __device__ __forceinline__ unsigned cvt_pk_bf16(float lo, float hi) { const f32x2_t v = {lo, hi}; const bf16x2_t r = __builtin_convertvector(v, bf16x2_t); return __builtin_bit_cast(unsigned, r); }
; __device__ __forceinline__ float bf_lo(unsigned w) { return __uint_as_float(w << 16); }
; __device__ __forceinline__ float bf_hi(unsigned w) { return __uint_as_float(w & 0xffff0000u); }
;     __device__ __forceinline__ void operator()(const f32x4 (&acc)[2][2][4][2], const Unit& u, int wr, int wc, int fr, int fq) const {
;     ...
;             for (int m = 0; m < 4; ++m) { const size_t off = (size_t)(row0 + ai * HALF + m * 16) * 1024 + col0;
; #pragma unroll
;                 for (int bj = 0; bj < 2; ++bj) { const f32x4 v0 = acc[ai][bj][m][0], v1 = acc[ai][bj][m][1];
;                     const u32x4 ga = *(const u32x4*)(GA + off + bj * HALF); u32x4 w;
;                     if (MODE == 0) {
;                         w.x = cvt_pk_bf16(v0[0] * bf_lo(ga.x), v0[1] * bf_hi(ga.x)); w.y = cvt_pk_bf16(v0[2] * bf_lo(ga.y), v0[3] * bf_hi(ga.y));
;                         w.z = cvt_pk_bf16(v1[0] * bf_lo(ga.z), v1[1] * bf_hi(ga.z)); w.w = cvt_pk_bf16(v1[2] * bf_lo(ga.w), v1[3] * bf_hi(ga.w));
;                         *(u32x4*)(GA + off + bj * HALF) = w;
;                     } else {
;                         const u32x4 gb = *(const u32x4*)(GB + off + bj * HALF);
;                         w.x = cvt_pk_bf16(bf_lo(ga.x) + v0[0] * bf_lo(gb.x), bf_hi(ga.x) + v0[1] * bf_hi(gb.x)); w.y = cvt_pk_bf16(bf_lo(ga.y) + v0[2] * bf_lo(gb.y), bf_hi(ga.y) + v0[3] * bf_hi(gb.y));
;                         w.z = cvt_pk_bf16(bf_lo(ga.z) + v1[0] * bf_lo(gb.z), bf_hi(ga.z) + v1[1] * bf_hi(gb.z)); w.w = cvt_pk_bf16(bf_lo(ga.w) + v1[2] * bf_lo(gb.w), bf_hi(ga.w) + v1[3] * bf_hi(gb.w));
;                         *(u32x4*)(Y + off + bj * HALF) = w;
	v_lshlrev_b32_e32 v154, 16, v187
	v_and_b32_e32 v155, 0xffff0000, v187
	v_lshlrev_b32_e32 v156, 16, v191
	v_and_b32_e32 v157, 0xffff0000, v191
	v_pk_fma_f32 v[102:103], v[102:103], v[156:157], v[154:155]
	v_lshlrev_b32_e32 v154, 16, v188
	v_and_b32_e32 v155, 0xffff0000, v188
	v_lshlrev_b32_e32 v156, 16, v192
	v_and_b32_e32 v157, 0xffff0000, v192
	v_pk_fma_f32 v[96:97], v[96:97], v[156:157], v[154:155]
	v_lshlrev_b32_e32 v154, 16, v189
	v_and_b32_e32 v155, 0xffff0000, v189
	v_lshlrev_b32_e32 v156, 16, v193
	v_and_b32_e32 v157, 0xffff0000, v193
	v_pk_fma_f32 v[98:99], v[98:99], v[156:157], v[154:155]
	v_cvt_pk_bf16_f32 v100, v100, v101
	v_cvt_pk_bf16_f32 v101, v102, v103
	v_cvt_pk_bf16_f32 v102, v96, v97
	v_cvt_pk_bf16_f32 v103, v98, v99
	global_store_dwordx4 v[158:159], v[100:103], off offset:256
	s_mov_b64 s[14:15], 0x10000
	v_lshl_add_u64 v[158:159], v[138:139], 0, s[14:15]
	v_lshl_add_u64 v[158:159], v[158:159], 0, s[44:45]
	v_lshlrev_b32_e32 v154, 16, v194
	v_and_b32_e32 v155, 0xffff0000, v194
	v_lshlrev_b32_e32 v156, 16, v198
	v_and_b32_e32 v157, 0xffff0000, v198
	v_pk_fma_f32 v[92:93], v[92:93], v[156:157], v[154:155]
	v_lshlrev_b32_e32 v154, 16, v195
	v_and_b32_e32 v155, 0xffff0000, v195
	v_lshlrev_b32_e32 v156, 16, v199
	v_and_b32_e32 v157, 0xffff0000, v199
	v_pk_fma_f32 v[94:95], v[94:95], v[156:157], v[154:155]
	v_lshlrev_b32_e32 v154, 16, v196
	v_and_b32_e32 v155, 0xffff0000, v196
	v_lshlrev_b32_e32 v156, 16, v200
	v_and_b32_e32 v157, 0xffff0000, v200
	v_pk_fma_f32 v[88:89], v[88:89], v[156:157], v[154:155]
	v_lshlrev_b32_e32 v154, 16, v197
	v_and_b32_e32 v155, 0xffff0000, v197
	v_lshlrev_b32_e32 v156, 16, v201
	v_and_b32_e32 v157, 0xffff0000, v201
	v_pk_fma_f32 v[90:91], v[90:91], v[156:157], v[154:155]
	v_cvt_pk_bf16_f32 v92, v92, v93
	v_cvt_pk_bf16_f32 v93, v94, v95
	v_cvt_pk_bf16_f32 v94, v88, v89
	v_cvt_pk_bf16_f32 v95, v90, v91
	global_store_dwordx4 v[158:159], v[92:95], off
	v_lshlrev_b32_e32 v154, 16, v202
	v_and_b32_e32 v155, 0xffff0000, v202
	v_lshlrev_b32_e32 v156, 16, v206
	v_and_b32_e32 v157, 0xffff0000, v206
	v_pk_fma_f32 v[84:85], v[84:85], v[156:157], v[154:155]
	v_lshlrev_b32_e32 v154, 16, v203
	v_and_b32_e32 v155, 0xffff0000, v203
	v_lshlrev_b32_e32 v156, 16, v207
	v_and_b32_e32 v157, 0xffff0000, v207
	v_pk_fma_f32 v[86:87], v[86:87], v[156:157], v[154:155]
	v_lshlrev_b32_e32 v154, 16, v204
	v_and_b32_e32 v155, 0xffff0000, v204
	v_lshlrev_b32_e32 v156, 16, v208
	v_and_b32_e32 v157, 0xffff0000, v208
	v_pk_fma_f32 v[80:81], v[80:81], v[156:157], v[154:155]
	v_lshlrev_b32_e32 v154, 16, v205
	v_and_b32_e32 v155, 0xffff0000, v205
	v_lshlrev_b32_e32 v156, 16, v209
	v_and_b32_e32 v157, 0xffff0000, v209
	v_pk_fma_f32 v[82:83], v[82:83], v[156:157], v[154:155]
	v_cvt_pk_bf16_f32 v84, v84, v85
	v_cvt_pk_bf16_f32 v85, v86, v87
	v_cvt_pk_bf16_f32 v86, v80, v81
	v_cvt_pk_bf16_f32 v87, v82, v83
	global_store_dwordx4 v[158:159], v[84:87], off offset:256
	s_mov_b64 s[14:15], 0x18000
	v_lshl_add_u64 v[158:159], v[138:139], 0, s[14:15]
	v_lshl_add_u64 v[158:159], v[158:159], 0, s[44:45]
	v_lshlrev_b32_e32 v154, 16, v210
	v_and_b32_e32 v155, 0xffff0000, v210
	v_lshlrev_b32_e32 v156, 16, v146
	v_and_b32_e32 v157, 0xffff0000, v146
	v_pk_fma_f32 v[76:77], v[76:77], v[156:157], v[154:155]
	v_lshlrev_b32_e32 v154, 16, v211
	v_and_b32_e32 v155, 0xffff0000, v211
	v_lshlrev_b32_e32 v156, 16, v147
	v_and_b32_e32 v157, 0xffff0000, v147
	v_pk_fma_f32 v[78:79], v[78:79], v[156:157], v[154:155]
	v_lshlrev_b32_e32 v154, 16, v212
	v_and_b32_e32 v155, 0xffff0000, v212
	v_lshlrev_b32_e32 v156, 16, v148
	v_and_b32_e32 v157, 0xffff0000, v148
	v_pk_fma_f32 v[72:73], v[72:73], v[156:157], v[154:155]
	v_lshlrev_b32_e32 v154, 16, v213
	v_and_b32_e32 v155, 0xffff0000, v213
	v_lshlrev_b32_e32 v156, 16, v149
	v_and_b32_e32 v157, 0xffff0000, v149
	v_pk_fma_f32 v[74:75], v[74:75], v[156:157], v[154:155]
	v_cvt_pk_bf16_f32 v76, v76, v77
	v_cvt_pk_bf16_f32 v77, v78, v79
	v_cvt_pk_bf16_f32 v78, v72, v73
	v_cvt_pk_bf16_f32 v79, v74, v75
	global_store_dwordx4 v[158:159], v[76:79], off
	v_lshlrev_b32_e32 v154, 16, v150
	v_and_b32_e32 v155, 0xffff0000, v150
	v_lshlrev_b32_e32 v156, 16, v140
	v_and_b32_e32 v157, 0xffff0000, v140
	v_pk_fma_f32 v[68:69], v[68:69], v[156:157], v[154:155]
	v_lshlrev_b32_e32 v154, 16, v151
	v_and_b32_e32 v155, 0xffff0000, v151
	v_lshlrev_b32_e32 v156, 16, v141
	v_and_b32_e32 v157, 0xffff0000, v141
	v_pk_fma_f32 v[70:71], v[70:71], v[156:157], v[154:155]
	v_lshlrev_b32_e32 v154, 16, v152
	v_and_b32_e32 v155, 0xffff0000, v152
	v_lshlrev_b32_e32 v156, 16, v142
	v_and_b32_e32 v157, 0xffff0000, v142
	v_pk_fma_f32 v[64:65], v[64:65], v[156:157], v[154:155]
	v_lshlrev_b32_e32 v154, 16, v153
	v_and_b32_e32 v155, 0xffff0000, v153
	v_lshlrev_b32_e32 v156, 16, v143
	v_and_b32_e32 v157, 0xffff0000, v143
	v_pk_fma_f32 v[66:67], v[66:67], v[156:157], v[154:155]
	v_cvt_pk_bf16_f32 v68, v68, v69
	v_cvt_pk_bf16_f32 v69, v70, v71
	v_cvt_pk_bf16_f32 v70, v64, v65
	v_cvt_pk_bf16_f32 v71, v66, v67
	global_store_dwordx4 v[158:159], v[68:71], off offset:256
	s_mov_b64 s[14:15], 0x40000
	v_lshl_add_u64 v[158:159], v[138:139], 0, s[14:15]
	v_lshl_add_u64 v[154:155], v[158:159], 0, s[24:25]
	v_lshl_add_u64 v[156:157], v[158:159], 0, s[38:39]
	global_load_dwordx4 v[162:165], v[154:155], off
	global_load_dwordx4 v[166:169], v[156:157], off
	global_load_dwordx4 v[170:173], v[154:155], off offset:256
	global_load_dwordx4 v[174:177], v[156:157], off offset:256
	s_mov_b64 s[14:15], 0x48000
	v_lshl_add_u64 v[158:159], v[138:139], 0, s[14:15]
	v_lshl_add_u64 v[154:155], v[158:159], 0, s[24:25]
	v_lshl_add_u64 v[156:157], v[158:159], 0, s[38:39]
	global_load_dwordx4 v[178:181], v[154:155], off
	global_load_dwordx4 v[182:185], v[156:157], off
	global_load_dwordx4 v[186:189], v[154:155], off offset:256
	global_load_dwordx4 v[190:193], v[156:157], off offset:256
	s_mov_b64 s[14:15], 0x50000
	v_lshl_add_u64 v[158:159], v[138:139], 0, s[14:15]
	v_lshl_add_u64 v[154:155], v[158:159], 0, s[24:25]
	v_lshl_add_u64 v[156:157], v[158:159], 0, s[38:39]
	global_load_dwordx4 v[194:197], v[154:155], off
	global_load_dwordx4 v[198:201], v[156:157], off
	global_load_dwordx4 v[202:205], v[154:155], off offset:256
	global_load_dwordx4 v[206:209], v[156:157], off offset:256
	s_mov_b64 s[14:15], 0x58000
	v_lshl_add_u64 v[158:159], v[138:139], 0, s[14:15]
	v_lshl_add_u64 v[154:155], v[158:159], 0, s[24:25]
	v_lshl_add_u64 v[156:157], v[158:159], 0, s[38:39]
	global_load_dwordx4 v[210:213], v[154:155], off
	global_load_dwordx4 v[146:149], v[156:157], off
	global_load_dwordx4 v[150:153], v[154:155], off offset:256
	global_load_dwordx4 v[140:143], v[156:157], off offset:256
	s_waitcnt vmcnt(0) lgkmcnt(0)
; __device__ __forceinline__ unsigned cvt_pk_bf16(float lo, float hi) { const f32x2_t v = {lo, hi}; const bf16x2_t r = __builtin_convertvector(v, bf16x2_t); return __builtin_bit_cast(unsigned, r); }
; __device__ __forceinline__ float bf_lo(unsigned w) { return __uint_as_float(w << 16); }
; __device__ __forceinline__ float bf_hi(unsigned w) { return __uint_as_float(w & 0xffff0000u); }
;     __device__ __forceinline__ void operator()(const f32x4 (&acc)[2][2][4][2], const Unit& u, int wr, int wc, int fr, int fq) const {
;     ...
;             for (int m = 0; m < 4; ++m) { const size_t off = (size_t)(row0 + ai * HALF + m * 16) * 1024 + col0;
; #pragma unroll
;                 for (int bj = 0; bj < 2; ++bj) { const f32x4 v0 = acc[ai][bj][m][0], v1 = acc[ai][bj][m][1];
;                     const u32x4 ga = *(const u32x4*)(GA + off + bj * HALF); u32x4 w;
;                     if (MODE == 0) {
;                         w.x = cvt_pk_bf16(v0[0] * bf_lo(ga.x), v0[1] * bf_hi(ga.x)); w.y = cvt_pk_bf16(v0[2] * bf_lo(ga.y), v0[3] * bf_hi(ga.y));
;                         w.z = cvt_pk_bf16(v1[0] * bf_lo(ga.z), v1[1] * bf_hi(ga.z)); w.w = cvt_pk_bf16(v1[2] * bf_lo(ga.w), v1[3] * bf_hi(ga.w));
;                         *(u32x4*)(GA + off + bj * HALF) = w;
;                     } else {
;                         const u32x4 gb = *(const u32x4*)(GB + off + bj * HALF);
;                         w.x = cvt_pk_bf16(bf_lo(ga.x) + v0[0] * bf_lo(gb.x), bf_hi(ga.x) + v0[1] * bf_hi(gb.x)); w.y = cvt_pk_bf16(bf_lo(ga.y) + v0[2] * bf_lo(gb.y), bf_hi(ga.y) + v0[3] * bf_hi(gb.y));
;                         w.z = cvt_pk_bf16(bf_lo(ga.z) + v1[0] * bf_lo(gb.z), bf_hi(ga.z) + v1[1] * bf_hi(gb.z)); w.w = cvt_pk_bf16(bf_lo(ga.w) + v1[2] * bf_lo(gb.w), bf_hi(ga.w) + v1[3] * bf_hi(gb.w));
;                         *(u32x4*)(Y + off + bj * HALF) = w;
	s_mov_b64 s[14:15], 0x40000
	v_lshl_add_u64 v[158:159], v[138:139], 0, s[14:15]
	v_lshl_add_u64 v[158:159], v[158:159], 0, s[44:45]
	v_lshlrev_b32_e32 v154, 16, v162
	v_and_b32_e32 v155, 0xffff0000, v162
	v_lshlrev_b32_e32 v156, 16, v166
	v_and_b32_e32 v157, 0xffff0000, v166
	v_pk_fma_f32 v[60:61], v[60:61], v[156:157], v[154:155]
	v_lshlrev_b32_e32 v154, 16, v163
	v_and_b32_e32 v155, 0xffff0000, v163
	v_lshlrev_b32_e32 v156, 16, v167
	v_and_b32_e32 v157, 0xffff0000, v167
	v_pk_fma_f32 v[62:63], v[62:63], v[156:157], v[154:155]
	v_lshlrev_b32_e32 v154, 16, v164
	v_and_b32_e32 v155, 0xffff0000, v164
	v_lshlrev_b32_e32 v156, 16, v168
	v_and_b32_e32 v157, 0xffff0000, v168
	v_pk_fma_f32 v[56:57], v[56:57], v[156:157], v[154:155]
	v_lshlrev_b32_e32 v154, 16, v165
	v_and_b32_e32 v155, 0xffff0000, v165
	v_lshlrev_b32_e32 v156, 16, v169
	v_and_b32_e32 v157, 0xffff0000, v169
	v_pk_fma_f32 v[58:59], v[58:59], v[156:157], v[154:155]
	v_cvt_pk_bf16_f32 v60, v60, v61
	v_cvt_pk_bf16_f32 v61, v62, v63
	v_cvt_pk_bf16_f32 v62, v56, v57
	v_cvt_pk_bf16_f32 v63, v58, v59
	global_store_dwordx4 v[158:159], v[60:63], off
	v_lshlrev_b32_e32 v154, 16, v170
	v_and_b32_e32 v155, 0xffff0000, v170
	v_lshlrev_b32_e32 v156, 16, v174
	v_and_b32_e32 v157, 0xffff0000, v174
	v_pk_fma_f32 v[52:53], v[52:53], v[156:157], v[154:155]
	v_lshlrev_b32_e32 v154, 16, v171
	v_and_b32_e32 v155, 0xffff0000, v171
	v_lshlrev_b32_e32 v156, 16, v175
	v_and_b32_e32 v157, 0xffff0000, v175
	v_pk_fma_f32 v[54:55], v[54:55], v[156:157], v[154:155]
	v_lshlrev_b32_e32 v154, 16, v172
	v_and_b32_e32 v155, 0xffff0000, v172
	v_lshlrev_b32_e32 v156, 16, v176
	v_and_b32_e32 v157, 0xffff0000, v176
	v_pk_fma_f32 v[48:49], v[48:49], v[156:157], v[154:155]
	v_lshlrev_b32_e32 v154, 16, v173
	v_and_b32_e32 v155, 0xffff0000, v173
	v_lshlrev_b32_e32 v156, 16, v177
	v_and_b32_e32 v157, 0xffff0000, v177
	v_pk_fma_f32 v[50:51], v[50:51], v[156:157], v[154:155]
	v_cvt_pk_bf16_f32 v52, v52, v53
	v_cvt_pk_bf16_f32 v53, v54, v55
	v_cvt_pk_bf16_f32 v54, v48, v49
	v_cvt_pk_bf16_f32 v55, v50, v51
	global_store_dwordx4 v[158:159], v[52:55], off offset:256
	s_mov_b64 s[14:15], 0x48000
	v_lshl_add_u64 v[158:159], v[138:139], 0, s[14:15]
	v_lshl_add_u64 v[158:159], v[158:159], 0, s[44:45]
	v_lshlrev_b32_e32 v154, 16, v178
	v_and_b32_e32 v155, 0xffff0000, v178
	v_lshlrev_b32_e32 v156, 16, v182
	v_and_b32_e32 v157, 0xffff0000, v182
	v_pk_fma_f32 v[44:45], v[44:45], v[156:157], v[154:155]
	v_lshlrev_b32_e32 v154, 16, v179
	v_and_b32_e32 v155, 0xffff0000, v179
	v_lshlrev_b32_e32 v156, 16, v183
	v_and_b32_e32 v157, 0xffff0000, v183
	v_pk_fma_f32 v[46:47], v[46:47], v[156:157], v[154:155]
	v_lshlrev_b32_e32 v154, 16, v180
	v_and_b32_e32 v155, 0xffff0000, v180
	v_lshlrev_b32_e32 v156, 16, v184
	v_and_b32_e32 v157, 0xffff0000, v184
	v_pk_fma_f32 v[40:41], v[40:41], v[156:157], v[154:155]
	v_lshlrev_b32_e32 v154, 16, v181
	v_and_b32_e32 v155, 0xffff0000, v181
	v_lshlrev_b32_e32 v156, 16, v185
	v_and_b32_e32 v157, 0xffff0000, v185
	v_pk_fma_f32 v[42:43], v[42:43], v[156:157], v[154:155]
	v_cvt_pk_bf16_f32 v44, v44, v45
	v_cvt_pk_bf16_f32 v45, v46, v47
	v_cvt_pk_bf16_f32 v46, v40, v41
	v_cvt_pk_bf16_f32 v47, v42, v43
	global_store_dwordx4 v[158:159], v[44:47], off
	v_lshlrev_b32_e32 v154, 16, v186
	v_and_b32_e32 v155, 0xffff0000, v186
	v_lshlrev_b32_e32 v156, 16, v190
	v_and_b32_e32 v157, 0xffff0000, v190
	v_pk_fma_f32 v[36:37], v[36:37], v[156:157], v[154:155]
	v_lshlrev_b32_e32 v154, 16, v187
	v_and_b32_e32 v155, 0xffff0000, v187
	v_lshlrev_b32_e32 v156, 16, v191
	v_and_b32_e32 v157, 0xffff0000, v191
	v_pk_fma_f32 v[38:39], v[38:39], v[156:157], v[154:155]
	v_lshlrev_b32_e32 v154, 16, v188
	v_and_b32_e32 v155, 0xffff0000, v188
	v_lshlrev_b32_e32 v156, 16, v192
	v_and_b32_e32 v157, 0xffff0000, v192
	v_pk_fma_f32 v[32:33], v[32:33], v[156:157], v[154:155]
	v_lshlrev_b32_e32 v154, 16, v189
	v_and_b32_e32 v155, 0xffff0000, v189
	v_lshlrev_b32_e32 v156, 16, v193
	v_and_b32_e32 v157, 0xffff0000, v193
	v_pk_fma_f32 v[34:35], v[34:35], v[156:157], v[154:155]
	v_cvt_pk_bf16_f32 v36, v36, v37
	v_cvt_pk_bf16_f32 v37, v38, v39
	v_cvt_pk_bf16_f32 v38, v32, v33
	v_cvt_pk_bf16_f32 v39, v34, v35
	global_store_dwordx4 v[158:159], v[36:39], off offset:256
	s_mov_b64 s[14:15], 0x50000
; __device__ __forceinline__ unsigned cvt_pk_bf16(float lo, float hi) { const f32x2_t v = {lo, hi}; const bf16x2_t r = __builtin_convertvector(v, bf16x2_t); return __builtin_bit_cast(unsigned, r); }
; __device__ __forceinline__ float bf_lo(unsigned w) { return __uint_as_float(w << 16); }
; __device__ __forceinline__ float bf_hi(unsigned w) { return __uint_as_float(w & 0xffff0000u); }
;     __device__ __forceinline__ void operator()(const f32x4 (&acc)[2][2][4][2], const Unit& u, int wr, int wc, int fr, int fq) const {
;     ...
;             for (int m = 0; m < 4; ++m) { const size_t off = (size_t)(row0 + ai * HALF + m * 16) * 1024 + col0;
; #pragma unroll
;                 for (int bj = 0; bj < 2; ++bj) { const f32x4 v0 = acc[ai][bj][m][0], v1 = acc[ai][bj][m][1];
;                     const u32x4 ga = *(const u32x4*)(GA + off + bj * HALF); u32x4 w;
;                     if (MODE == 0) {
;                         w.x = cvt_pk_bf16(v0[0] * bf_lo(ga.x), v0[1] * bf_hi(ga.x)); w.y = cvt_pk_bf16(v0[2] * bf_lo(ga.y), v0[3] * bf_hi(ga.y));
;                         w.z = cvt_pk_bf16(v1[0] * bf_lo(ga.z), v1[1] * bf_hi(ga.z)); w.w = cvt_pk_bf16(v1[2] * bf_lo(ga.w), v1[3] * bf_hi(ga.w));
;                         *(u32x4*)(GA + off + bj * HALF) = w;
;                     } else {
;                         const u32x4 gb = *(const u32x4*)(GB + off + bj * HALF);
;                         w.x = cvt_pk_bf16(bf_lo(ga.x) + v0[0] * bf_lo(gb.x), bf_hi(ga.x) + v0[1] * bf_hi(gb.x)); w.y = cvt_pk_bf16(bf_lo(ga.y) + v0[2] * bf_lo(gb.y), bf_hi(ga.y) + v0[3] * bf_hi(gb.y));
;                         w.z = cvt_pk_bf16(bf_lo(ga.z) + v1[0] * bf_lo(gb.z), bf_hi(ga.z) + v1[1] * bf_hi(gb.z)); w.w = cvt_pk_bf16(bf_lo(ga.w) + v1[2] * bf_lo(gb.w), bf_hi(ga.w) + v1[3] * bf_hi(gb.w));
;                         *(u32x4*)(Y + off + bj * HALF) = w;
;                     } } }
	v_lshl_add_u64 v[158:159], v[138:139], 0, s[14:15]
	v_lshl_add_u64 v[158:159], v[158:159], 0, s[44:45]
	v_lshlrev_b32_e32 v154, 16, v194
	v_and_b32_e32 v155, 0xffff0000, v194
	v_lshlrev_b32_e32 v156, 16, v198
	v_and_b32_e32 v157, 0xffff0000, v198
	v_pk_fma_f32 v[28:29], v[28:29], v[156:157], v[154:155]
	v_lshlrev_b32_e32 v154, 16, v195
	v_and_b32_e32 v155, 0xffff0000, v195
	v_lshlrev_b32_e32 v156, 16, v199
	v_and_b32_e32 v157, 0xffff0000, v199
	v_pk_fma_f32 v[30:31], v[30:31], v[156:157], v[154:155]
	v_lshlrev_b32_e32 v154, 16, v196
	v_and_b32_e32 v155, 0xffff0000, v196
	v_lshlrev_b32_e32 v156, 16, v200
	v_and_b32_e32 v157, 0xffff0000, v200
	v_pk_fma_f32 v[24:25], v[24:25], v[156:157], v[154:155]
	v_lshlrev_b32_e32 v154, 16, v197
	v_and_b32_e32 v155, 0xffff0000, v197
	v_lshlrev_b32_e32 v156, 16, v201
	v_and_b32_e32 v157, 0xffff0000, v201
	v_pk_fma_f32 v[26:27], v[26:27], v[156:157], v[154:155]
	v_cvt_pk_bf16_f32 v28, v28, v29
	v_cvt_pk_bf16_f32 v29, v30, v31
	v_cvt_pk_bf16_f32 v30, v24, v25
	v_cvt_pk_bf16_f32 v31, v26, v27
	global_store_dwordx4 v[158:159], v[28:31], off
	v_lshlrev_b32_e32 v154, 16, v202
	v_and_b32_e32 v155, 0xffff0000, v202
	v_lshlrev_b32_e32 v156, 16, v206
	v_and_b32_e32 v157, 0xffff0000, v206
	v_pk_fma_f32 v[20:21], v[20:21], v[156:157], v[154:155]
	v_lshlrev_b32_e32 v154, 16, v203
	v_and_b32_e32 v155, 0xffff0000, v203
	v_lshlrev_b32_e32 v156, 16, v207
	v_and_b32_e32 v157, 0xffff0000, v207
	v_pk_fma_f32 v[22:23], v[22:23], v[156:157], v[154:155]
	v_lshlrev_b32_e32 v154, 16, v204
	v_and_b32_e32 v155, 0xffff0000, v204
	v_lshlrev_b32_e32 v156, 16, v208
	v_and_b32_e32 v157, 0xffff0000, v208
	v_pk_fma_f32 v[16:17], v[16:17], v[156:157], v[154:155]
	v_lshlrev_b32_e32 v154, 16, v205
	v_and_b32_e32 v155, 0xffff0000, v205
	v_lshlrev_b32_e32 v156, 16, v209
	v_and_b32_e32 v157, 0xffff0000, v209
	v_pk_fma_f32 v[18:19], v[18:19], v[156:157], v[154:155]
	v_cvt_pk_bf16_f32 v20, v20, v21
	v_cvt_pk_bf16_f32 v21, v22, v23
	v_cvt_pk_bf16_f32 v22, v16, v17
	v_cvt_pk_bf16_f32 v23, v18, v19
	global_store_dwordx4 v[158:159], v[20:23], off offset:256
	s_mov_b64 s[14:15], 0x58000
	v_lshl_add_u64 v[158:159], v[138:139], 0, s[14:15]
	v_lshl_add_u64 v[158:159], v[158:159], 0, s[44:45]
	v_lshlrev_b32_e32 v154, 16, v210
	v_and_b32_e32 v155, 0xffff0000, v210
	v_lshlrev_b32_e32 v156, 16, v146
	v_and_b32_e32 v157, 0xffff0000, v146
	v_pk_fma_f32 v[12:13], v[12:13], v[156:157], v[154:155]
	v_lshlrev_b32_e32 v154, 16, v211
	v_and_b32_e32 v155, 0xffff0000, v211
	v_lshlrev_b32_e32 v156, 16, v147
	v_and_b32_e32 v157, 0xffff0000, v147
	v_pk_fma_f32 v[14:15], v[14:15], v[156:157], v[154:155]
	v_lshlrev_b32_e32 v154, 16, v212
	v_and_b32_e32 v155, 0xffff0000, v212
	v_lshlrev_b32_e32 v156, 16, v148
	v_and_b32_e32 v157, 0xffff0000, v148
	v_pk_fma_f32 v[8:9], v[8:9], v[156:157], v[154:155]
	v_lshlrev_b32_e32 v154, 16, v213
	v_and_b32_e32 v155, 0xffff0000, v213
	v_lshlrev_b32_e32 v156, 16, v149
	v_and_b32_e32 v157, 0xffff0000, v149
	v_pk_fma_f32 v[10:11], v[10:11], v[156:157], v[154:155]
	v_cvt_pk_bf16_f32 v12, v12, v13
	v_cvt_pk_bf16_f32 v13, v14, v15
	v_cvt_pk_bf16_f32 v14, v8, v9
	v_cvt_pk_bf16_f32 v15, v10, v11
	global_store_dwordx4 v[158:159], v[12:15], off
	v_lshlrev_b32_e32 v154, 16, v150
	v_and_b32_e32 v155, 0xffff0000, v150
	v_lshlrev_b32_e32 v156, 16, v140
	v_and_b32_e32 v157, 0xffff0000, v140
	v_pk_fma_f32 v[4:5], v[4:5], v[156:157], v[154:155]
	v_lshlrev_b32_e32 v154, 16, v151
	v_and_b32_e32 v155, 0xffff0000, v151
	v_lshlrev_b32_e32 v156, 16, v141
	v_and_b32_e32 v157, 0xffff0000, v141
	v_pk_fma_f32 v[6:7], v[6:7], v[156:157], v[154:155]
	v_lshlrev_b32_e32 v154, 16, v152
	v_and_b32_e32 v155, 0xffff0000, v152
	v_lshlrev_b32_e32 v156, 16, v142
	v_and_b32_e32 v157, 0xffff0000, v142
	v_pk_fma_f32 v[0:1], v[0:1], v[156:157], v[154:155]
	v_lshlrev_b32_e32 v154, 16, v153
	v_and_b32_e32 v155, 0xffff0000, v153
	v_lshlrev_b32_e32 v156, 16, v143
	v_and_b32_e32 v157, 0xffff0000, v143
	v_pk_fma_f32 v[2:3], v[2:3], v[156:157], v[154:155]
	v_cvt_pk_bf16_f32 v4, v4, v5
	v_cvt_pk_bf16_f32 v5, v6, v7
	v_cvt_pk_bf16_f32 v6, v0, v1
	v_cvt_pk_bf16_f32 v7, v2, v3
	global_store_dwordx4 v[158:159], v[4:7], off offset:256
	s_andn2_b64 vcc, exec, s[42:43]
	s_cbranch_vccnz .LBB0_97
	s_and_b64 vcc, exec, s[40:41]
	s_cbranch_vccnz .LBB0_96
	s_barrier
	s_branch .LBB0_96
